# P0 adaLN GEMV: inner loop unrolled and software-pipelined (3 load blocks in flight instead of 1)
# speedup vs baseline: 1.0154x; 1.0017x over previous
.LBB0_25:
	v_add_u32_e32 v36, -12, v24
	v_lshl_add_u64 v[38:39], v[8:9], 0, s[12:13]
	v_ashrrev_i32_e32 v37, 31, v36
	v_add_co_u32_e32 v42, vcc, s15, v38
	v_add_u32_e32 v25, -8, v24
	v_lshl_add_u64 v[26:27], v[6:7], 0, s[12:13]
	v_add_u32_e32 v35, -4, v24
	v_mad_i64_i32 v[28:29], s[18:19], v36, s14, v[18:19]
	v_addc_co_u32_e32 v43, vcc, 0, v39, vcc
	v_lshlrev_b64 v[36:37], 2, v[36:37]
	v_mad_i64_i32 v[40:41], s[18:19], v25, s14, v[18:19]
	global_load_dword v25, v[38:39], off offset:16
	global_load_dword v49, v[26:27], off offset:16
	v_mad_i64_i32 v[46:47], s[18:19], v35, s14, v[18:19]
	global_load_dword v35, v[38:39], off offset:32
	global_load_dword v51, v[26:27], off offset:32
	global_load_dword v53, v[26:27], off offset:48
	global_load_dword v55, v[42:43], off offset:16
	s_nop 0
	global_load_dwordx4 v[26:29], v[28:29], off
	s_nop 0
	global_load_dword v57, v[42:43], off offset:32
	global_load_dword v59, v[42:43], off offset:48
	global_load_dword v61, v[38:39], off offset:48
	v_lshl_add_u64 v[38:39], s[38:39], 0, v[36:37]
	v_lshl_add_u64 v[36:37], s[42:43], 0, v[36:37]
	global_load_dword v63, v[38:39], off
	global_load_dword v65, v[36:37], off
	v_add_co_u32_e32 v36, vcc, s15, v38
	v_mad_i64_i32 v[44:45], s[18:19], v24, s14, v[18:19]
	s_nop 0
	v_addc_co_u32_e32 v37, vcc, 0, v39, vcc
	global_load_dword v67, v[36:37], off
	s_nop 0
	global_load_dwordx4 v[36:39], v[40:41], off
	s_nop 0
	global_load_dwordx4 v[40:43], v[46:47], off
	s_nop 0
	global_load_dwordx4 v[44:47], v[44:45], off
	s_add_u32 s12, s12, 64
	s_addc_u32 s13, s13, 0
	v_add_u32_e32 v24, 16, v24
	v_add_u32_e32 v84, -12, v24
	v_lshl_add_u64 v[86:87], v[8:9], 0, s[12:13]
	v_ashrrev_i32_e32 v85, 31, v84
	v_add_co_u32_e32 v90, vcc, s15, v86
	v_add_u32_e32 v73, -8, v24
	v_lshl_add_u64 v[74:75], v[6:7], 0, s[12:13]
	v_add_u32_e32 v83, -4, v24
	v_mad_i64_i32 v[76:77], s[18:19], v84, s14, v[18:19]
	v_addc_co_u32_e32 v91, vcc, 0, v87, vcc
	v_lshlrev_b64 v[84:85], 2, v[84:85]
	v_mad_i64_i32 v[88:89], s[18:19], v73, s14, v[18:19]
	global_load_dword v73, v[86:87], off offset:16
	global_load_dword v97, v[74:75], off offset:16
	v_mad_i64_i32 v[94:95], s[18:19], v83, s14, v[18:19]
	global_load_dword v83, v[86:87], off offset:32
	global_load_dword v99, v[74:75], off offset:32
	global_load_dword v101, v[74:75], off offset:48
	global_load_dword v103, v[90:91], off offset:16
	s_nop 0
	global_load_dwordx4 v[74:77], v[76:77], off
	s_nop 0
	global_load_dword v105, v[90:91], off offset:32
	global_load_dword v107, v[90:91], off offset:48
	global_load_dword v109, v[86:87], off offset:48
	v_lshl_add_u64 v[86:87], s[38:39], 0, v[84:85]
	v_lshl_add_u64 v[84:85], s[42:43], 0, v[84:85]
	global_load_dword v111, v[86:87], off
	global_load_dword v113, v[84:85], off
	v_add_co_u32_e32 v84, vcc, s15, v86
	v_mad_i64_i32 v[92:93], s[18:19], v24, s14, v[18:19]
	s_nop 0
	v_addc_co_u32_e32 v85, vcc, 0, v87, vcc
	global_load_dword v115, v[84:85], off
	s_nop 0
	global_load_dwordx4 v[84:87], v[88:89], off
	s_nop 0
	global_load_dwordx4 v[88:91], v[94:95], off
	s_nop 0
	global_load_dwordx4 v[92:95], v[92:93], off
	s_add_u32 s12, s12, 64
	s_addc_u32 s13, s13, 0
	v_add_u32_e32 v24, 16, v24
	v_add_u32_e32 v132, -12, v24
	v_lshl_add_u64 v[134:135], v[8:9], 0, s[12:13]
	v_ashrrev_i32_e32 v133, 31, v132
	v_add_co_u32_e32 v138, vcc, s15, v134
	v_add_u32_e32 v121, -8, v24
	v_lshl_add_u64 v[122:123], v[6:7], 0, s[12:13]
	v_add_u32_e32 v131, -4, v24
	v_mad_i64_i32 v[124:125], s[18:19], v132, s14, v[18:19]
	v_addc_co_u32_e32 v139, vcc, 0, v135, vcc
	v_lshlrev_b64 v[132:133], 2, v[132:133]
	v_mad_i64_i32 v[136:137], s[18:19], v121, s14, v[18:19]
	global_load_dword v121, v[134:135], off offset:16
	global_load_dword v145, v[122:123], off offset:16
	v_mad_i64_i32 v[142:143], s[18:19], v131, s14, v[18:19]
	global_load_dword v131, v[134:135], off offset:32
	global_load_dword v147, v[122:123], off offset:32
	global_load_dword v149, v[122:123], off offset:48
	global_load_dword v151, v[138:139], off offset:16
	s_nop 0
	global_load_dwordx4 v[122:125], v[124:125], off
	s_nop 0
	global_load_dword v153, v[138:139], off offset:32
	global_load_dword v155, v[138:139], off offset:48
	global_load_dword v157, v[134:135], off offset:48
	v_lshl_add_u64 v[134:135], s[38:39], 0, v[132:133]
	v_lshl_add_u64 v[132:133], s[42:43], 0, v[132:133]
	global_load_dword v159, v[134:135], off
	global_load_dword v161, v[132:133], off
	v_add_co_u32_e32 v132, vcc, s15, v134
	v_mad_i64_i32 v[140:141], s[18:19], v24, s14, v[18:19]
	s_nop 0
	v_addc_co_u32_e32 v133, vcc, 0, v135, vcc
	global_load_dword v163, v[132:133], off
	s_nop 0
	global_load_dwordx4 v[132:135], v[136:137], off
	s_nop 0
	global_load_dwordx4 v[136:139], v[142:143], off
	s_nop 0
	global_load_dwordx4 v[140:143], v[140:141], off
	s_add_u32 s12, s12, 64
	s_addc_u32 s13, s13, 0
	v_add_u32_e32 v24, 16, v24
	s_waitcnt vmcnt(47)
	v_mul_f32_e32 v48, 0xbfb8aa3b, v25
	s_waitcnt vmcnt(46)
	v_mul_f32_e32 v50, 0xbfb8aa3b, v49
	s_waitcnt vmcnt(42)
	v_mul_f32_e32 v58, 0xbfb8aa3b, v55
	v_mul_f32_e32 v52, 0xbfb8aa3b, v35
	v_mul_f32_e32 v54, 0xbfb8aa3b, v51
	v_exp_f32_e32 v48, v48
	v_exp_f32_e32 v50, v50
	s_waitcnt vmcnt(37)
	v_mul_f32_e32 v66, 0xbfb8aa3b, v63
	s_waitcnt vmcnt(36)
	v_mul_f32_e32 v68, 0xbfb8aa3b, v65
	v_exp_f32_e32 v66, v66
	v_exp_f32_e32 v68, v68
	v_mul_f32_e32 v60, 0xbfb8aa3b, v57
	s_waitcnt vmcnt(35)
	v_mul_f32_e32 v69, 0xbfb8aa3b, v67
	v_exp_f32_e32 v69, v69
	v_exp_f32_e32 v58, v58
	v_mul_f32_e32 v56, 0xbfb8aa3b, v53
	v_exp_f32_e32 v52, v52
	v_exp_f32_e32 v54, v54
	v_mul_f32_e32 v62, 0xbfb8aa3b, v61
	v_mul_f32_e32 v64, 0xbfb8aa3b, v59
	v_exp_f32_e32 v60, v60
	v_exp_f32_e32 v56, v56
	v_exp_f32_e32 v62, v62
	v_exp_f32_e32 v64, v64
	v_add_f32_e32 v66, 1.0, v66
	v_add_f32_e32 v68, 1.0, v68
	v_add_f32_e32 v69, 1.0, v69
	v_add_f32_e32 v48, 1.0, v48
	v_add_f32_e32 v50, 1.0, v50
	v_add_f32_e32 v58, 1.0, v58
	v_rcp_f32_e32 v66, v66
	v_rcp_f32_e32 v68, v68
	v_rcp_f32_e32 v69, v69
	v_add_f32_e32 v52, 1.0, v52
	v_add_f32_e32 v54, 1.0, v54
	v_rcp_f32_e32 v48, v48
	v_rcp_f32_e32 v50, v50
	v_add_f32_e32 v60, 1.0, v60
	v_rcp_f32_e32 v58, v58
	v_add_f32_e32 v56, 1.0, v56
	v_rcp_f32_e32 v52, v52
	v_rcp_f32_e32 v54, v54
	v_add_f32_e32 v62, 1.0, v62
	v_add_f32_e32 v64, 1.0, v64
	v_rcp_f32_e32 v60, v60
	v_rcp_f32_e32 v56, v56
	v_rcp_f32_e32 v62, v62
	v_rcp_f32_e32 v64, v64
	v_mul_f32_e32 v66, v63, v66
	v_mul_f32_e32 v68, v65, v68
	v_mul_f32_e32 v70, v67, v69
	v_mul_f32_e32 v48, v25, v48
	v_mul_f32_e32 v50, v49, v50
	v_mul_f32_e32 v58, v55, v58
	v_pk_fma_f32 v[22:23], v[26:27], v[66:67], v[22:23] op_sel_hi:[1,0,1]
	v_pk_fma_f32 v[12:13], v[26:27], v[68:69], v[12:13] op_sel_hi:[1,0,1]
	v_pk_fma_f32 v[20:21], v[28:29], v[66:67], v[20:21] op_sel_hi:[1,0,1]
	v_pk_fma_f32 v[10:11], v[28:29], v[68:69], v[10:11] op_sel_hi:[1,0,1]
	v_pk_fma_f32 v[16:17], v[26:27], v[70:71], v[16:17] op_sel_hi:[1,0,1]
	v_pk_fma_f32 v[14:15], v[28:29], v[70:71], v[14:15] op_sel_hi:[1,0,1]
	v_mul_f32_e32 v52, v35, v52
	v_mul_f32_e32 v54, v51, v54
	v_mul_f32_e32 v60, v57, v60
	s_waitcnt vmcnt(34)
	v_pk_fma_f32 v[22:23], v[36:37], v[48:49], v[22:23] op_sel_hi:[1,0,1]
	v_pk_fma_f32 v[12:13], v[36:37], v[50:51], v[12:13] op_sel_hi:[1,0,1]
	v_pk_fma_f32 v[20:21], v[38:39], v[48:49], v[20:21] op_sel_hi:[1,0,1]
	v_pk_fma_f32 v[10:11], v[38:39], v[50:51], v[10:11] op_sel_hi:[1,0,1]
	v_pk_fma_f32 v[16:17], v[36:37], v[58:59], v[16:17] op_sel_hi:[1,0,1]
	v_pk_fma_f32 v[14:15], v[38:39], v[58:59], v[14:15] op_sel_hi:[1,0,1]
	v_mul_f32_e32 v56, v53, v56
	v_mul_f32_e32 v62, v61, v62
	v_mul_f32_e32 v64, v59, v64
	s_waitcnt vmcnt(33)
	v_pk_fma_f32 v[22:23], v[40:41], v[52:53], v[22:23] op_sel_hi:[1,0,1]
	v_pk_fma_f32 v[12:13], v[40:41], v[54:55], v[12:13] op_sel_hi:[1,0,1]
	v_pk_fma_f32 v[20:21], v[42:43], v[52:53], v[20:21] op_sel_hi:[1,0,1]
	v_pk_fma_f32 v[10:11], v[42:43], v[54:55], v[10:11] op_sel_hi:[1,0,1]
	v_pk_fma_f32 v[16:17], v[40:41], v[60:61], v[16:17] op_sel_hi:[1,0,1]
	v_pk_fma_f32 v[14:15], v[42:43], v[60:61], v[14:15] op_sel_hi:[1,0,1]
	s_waitcnt vmcnt(32)
	v_pk_fma_f32 v[22:23], v[44:45], v[62:63], v[22:23] op_sel_hi:[1,0,1]
	v_pk_fma_f32 v[12:13], v[44:45], v[56:57], v[12:13] op_sel_hi:[1,0,1]
	v_pk_fma_f32 v[20:21], v[46:47], v[62:63], v[20:21] op_sel_hi:[1,0,1]
	v_pk_fma_f32 v[10:11], v[46:47], v[56:57], v[10:11] op_sel_hi:[1,0,1]
	v_pk_fma_f32 v[16:17], v[44:45], v[64:65], v[16:17] op_sel_hi:[1,0,1]
	v_pk_fma_f32 v[14:15], v[46:47], v[64:65], v[14:15] op_sel_hi:[1,0,1]
	v_add_u32_e32 v36, -12, v24
	v_lshl_add_u64 v[38:39], v[8:9], 0, s[12:13]
	v_ashrrev_i32_e32 v37, 31, v36
	v_add_co_u32_e32 v42, vcc, s15, v38
	v_add_u32_e32 v25, -8, v24
	v_lshl_add_u64 v[26:27], v[6:7], 0, s[12:13]
	v_add_u32_e32 v35, -4, v24
	v_mad_i64_i32 v[28:29], s[18:19], v36, s14, v[18:19]
	v_addc_co_u32_e32 v43, vcc, 0, v39, vcc
	v_lshlrev_b64 v[36:37], 2, v[36:37]
	v_mad_i64_i32 v[40:41], s[18:19], v25, s14, v[18:19]
	global_load_dword v25, v[38:39], off offset:16
	global_load_dword v49, v[26:27], off offset:16
	v_mad_i64_i32 v[46:47], s[18:19], v35, s14, v[18:19]
	global_load_dword v35, v[38:39], off offset:32
	global_load_dword v51, v[26:27], off offset:32
	global_load_dword v53, v[26:27], off offset:48
	global_load_dword v55, v[42:43], off offset:16
	s_nop 0
	global_load_dwordx4 v[26:29], v[28:29], off
	s_nop 0
	global_load_dword v57, v[42:43], off offset:32
	global_load_dword v59, v[42:43], off offset:48
	global_load_dword v61, v[38:39], off offset:48
	v_lshl_add_u64 v[38:39], s[38:39], 0, v[36:37]
	v_lshl_add_u64 v[36:37], s[42:43], 0, v[36:37]
	global_load_dword v63, v[38:39], off
	global_load_dword v65, v[36:37], off
	v_add_co_u32_e32 v36, vcc, s15, v38
	v_mad_i64_i32 v[44:45], s[18:19], v24, s14, v[18:19]
	s_nop 0
	v_addc_co_u32_e32 v37, vcc, 0, v39, vcc
	global_load_dword v67, v[36:37], off
	s_nop 0
	global_load_dwordx4 v[36:39], v[40:41], off
	s_nop 0
	global_load_dwordx4 v[40:43], v[46:47], off
	s_nop 0
	global_load_dwordx4 v[44:47], v[44:45], off
	s_add_u32 s12, s12, 64
	s_addc_u32 s13, s13, 0
	v_add_u32_e32 v24, 16, v24
	s_waitcnt vmcnt(47)
	v_mul_f32_e32 v96, 0xbfb8aa3b, v73
	s_waitcnt vmcnt(46)
	v_mul_f32_e32 v98, 0xbfb8aa3b, v97
	s_waitcnt vmcnt(42)
	v_mul_f32_e32 v106, 0xbfb8aa3b, v103
	v_mul_f32_e32 v100, 0xbfb8aa3b, v83
	v_mul_f32_e32 v102, 0xbfb8aa3b, v99
	v_exp_f32_e32 v96, v96
	v_exp_f32_e32 v98, v98
	s_waitcnt vmcnt(37)
	v_mul_f32_e32 v114, 0xbfb8aa3b, v111
	s_waitcnt vmcnt(36)
	v_mul_f32_e32 v116, 0xbfb8aa3b, v113
	v_exp_f32_e32 v114, v114
	v_exp_f32_e32 v116, v116
	v_mul_f32_e32 v108, 0xbfb8aa3b, v105
	s_waitcnt vmcnt(35)
	v_mul_f32_e32 v117, 0xbfb8aa3b, v115
	v_exp_f32_e32 v117, v117
	v_exp_f32_e32 v106, v106
	v_mul_f32_e32 v104, 0xbfb8aa3b, v101
	v_exp_f32_e32 v100, v100
	v_exp_f32_e32 v102, v102
	v_mul_f32_e32 v110, 0xbfb8aa3b, v109
	v_mul_f32_e32 v112, 0xbfb8aa3b, v107
	v_exp_f32_e32 v108, v108
	v_exp_f32_e32 v104, v104
	v_exp_f32_e32 v110, v110
	v_exp_f32_e32 v112, v112
	v_add_f32_e32 v114, 1.0, v114
	v_add_f32_e32 v116, 1.0, v116
	v_add_f32_e32 v117, 1.0, v117
	v_add_f32_e32 v96, 1.0, v96
	v_add_f32_e32 v98, 1.0, v98
	v_add_f32_e32 v106, 1.0, v106
	v_rcp_f32_e32 v114, v114
	v_rcp_f32_e32 v116, v116
	v_rcp_f32_e32 v117, v117
	v_add_f32_e32 v100, 1.0, v100
	v_add_f32_e32 v102, 1.0, v102
	v_rcp_f32_e32 v96, v96
	v_rcp_f32_e32 v98, v98
	v_add_f32_e32 v108, 1.0, v108
	v_rcp_f32_e32 v106, v106
	v_add_f32_e32 v104, 1.0, v104
	v_rcp_f32_e32 v100, v100
	v_rcp_f32_e32 v102, v102
	v_add_f32_e32 v110, 1.0, v110
	v_add_f32_e32 v112, 1.0, v112
	v_rcp_f32_e32 v108, v108
	v_rcp_f32_e32 v104, v104
	v_rcp_f32_e32 v110, v110
	v_rcp_f32_e32 v112, v112
	v_mul_f32_e32 v114, v111, v114
	v_mul_f32_e32 v116, v113, v116
	v_mul_f32_e32 v118, v115, v117
	v_mul_f32_e32 v96, v73, v96
	v_mul_f32_e32 v98, v97, v98
	v_mul_f32_e32 v106, v103, v106
	v_pk_fma_f32 v[22:23], v[74:75], v[114:115], v[22:23] op_sel_hi:[1,0,1]
	v_pk_fma_f32 v[12:13], v[74:75], v[116:117], v[12:13] op_sel_hi:[1,0,1]
	v_pk_fma_f32 v[20:21], v[76:77], v[114:115], v[20:21] op_sel_hi:[1,0,1]
	v_pk_fma_f32 v[10:11], v[76:77], v[116:117], v[10:11] op_sel_hi:[1,0,1]
	v_pk_fma_f32 v[16:17], v[74:75], v[118:119], v[16:17] op_sel_hi:[1,0,1]
	v_pk_fma_f32 v[14:15], v[76:77], v[118:119], v[14:15] op_sel_hi:[1,0,1]
	v_mul_f32_e32 v100, v83, v100
	v_mul_f32_e32 v102, v99, v102
	v_mul_f32_e32 v108, v105, v108
	s_waitcnt vmcnt(34)
	v_pk_fma_f32 v[22:23], v[84:85], v[96:97], v[22:23] op_sel_hi:[1,0,1]
	v_pk_fma_f32 v[12:13], v[84:85], v[98:99], v[12:13] op_sel_hi:[1,0,1]
	v_pk_fma_f32 v[20:21], v[86:87], v[96:97], v[20:21] op_sel_hi:[1,0,1]
	v_pk_fma_f32 v[10:11], v[86:87], v[98:99], v[10:11] op_sel_hi:[1,0,1]
	v_pk_fma_f32 v[16:17], v[84:85], v[106:107], v[16:17] op_sel_hi:[1,0,1]
	v_pk_fma_f32 v[14:15], v[86:87], v[106:107], v[14:15] op_sel_hi:[1,0,1]
	v_mul_f32_e32 v104, v101, v104
	v_mul_f32_e32 v110, v109, v110
	v_mul_f32_e32 v112, v107, v112
	s_waitcnt vmcnt(33)
	v_pk_fma_f32 v[22:23], v[88:89], v[100:101], v[22:23] op_sel_hi:[1,0,1]
	v_pk_fma_f32 v[12:13], v[88:89], v[102:103], v[12:13] op_sel_hi:[1,0,1]
	v_pk_fma_f32 v[20:21], v[90:91], v[100:101], v[20:21] op_sel_hi:[1,0,1]
	v_pk_fma_f32 v[10:11], v[90:91], v[102:103], v[10:11] op_sel_hi:[1,0,1]
	v_pk_fma_f32 v[16:17], v[88:89], v[108:109], v[16:17] op_sel_hi:[1,0,1]
	v_pk_fma_f32 v[14:15], v[90:91], v[108:109], v[14:15] op_sel_hi:[1,0,1]
	s_waitcnt vmcnt(32)
	v_pk_fma_f32 v[22:23], v[92:93], v[110:111], v[22:23] op_sel_hi:[1,0,1]
	v_pk_fma_f32 v[12:13], v[92:93], v[104:105], v[12:13] op_sel_hi:[1,0,1]
	v_pk_fma_f32 v[20:21], v[94:95], v[110:111], v[20:21] op_sel_hi:[1,0,1]
	v_pk_fma_f32 v[10:11], v[94:95], v[104:105], v[10:11] op_sel_hi:[1,0,1]
	v_pk_fma_f32 v[16:17], v[92:93], v[112:113], v[16:17] op_sel_hi:[1,0,1]
	v_pk_fma_f32 v[14:15], v[94:95], v[112:113], v[14:15] op_sel_hi:[1,0,1]
	s_waitcnt vmcnt(31)
	v_mul_f32_e32 v144, 0xbfb8aa3b, v121
	s_waitcnt vmcnt(30)
	v_mul_f32_e32 v146, 0xbfb8aa3b, v145
	s_waitcnt vmcnt(26)
	v_mul_f32_e32 v154, 0xbfb8aa3b, v151
	v_mul_f32_e32 v148, 0xbfb8aa3b, v131
	v_mul_f32_e32 v150, 0xbfb8aa3b, v147
	v_exp_f32_e32 v144, v144
	v_exp_f32_e32 v146, v146
	s_waitcnt vmcnt(21)
	v_mul_f32_e32 v162, 0xbfb8aa3b, v159
	s_waitcnt vmcnt(20)
	v_mul_f32_e32 v164, 0xbfb8aa3b, v161
	v_exp_f32_e32 v162, v162
	v_exp_f32_e32 v164, v164
	v_mul_f32_e32 v156, 0xbfb8aa3b, v153
	s_waitcnt vmcnt(19)
	v_mul_f32_e32 v165, 0xbfb8aa3b, v163
	v_exp_f32_e32 v165, v165
	v_exp_f32_e32 v154, v154
	v_mul_f32_e32 v152, 0xbfb8aa3b, v149
	v_exp_f32_e32 v148, v148
	v_exp_f32_e32 v150, v150
	v_mul_f32_e32 v158, 0xbfb8aa3b, v157
	v_mul_f32_e32 v160, 0xbfb8aa3b, v155
	v_exp_f32_e32 v156, v156
	v_exp_f32_e32 v152, v152
	v_exp_f32_e32 v158, v158
	v_exp_f32_e32 v160, v160
	v_add_f32_e32 v162, 1.0, v162
	v_add_f32_e32 v164, 1.0, v164
	v_add_f32_e32 v165, 1.0, v165
	v_add_f32_e32 v144, 1.0, v144
	v_add_f32_e32 v146, 1.0, v146
	v_add_f32_e32 v154, 1.0, v154
	v_rcp_f32_e32 v162, v162
	v_rcp_f32_e32 v164, v164
	v_rcp_f32_e32 v165, v165
	v_add_f32_e32 v148, 1.0, v148
	v_add_f32_e32 v150, 1.0, v150
	v_rcp_f32_e32 v144, v144
	v_rcp_f32_e32 v146, v146
	v_add_f32_e32 v156, 1.0, v156
	v_rcp_f32_e32 v154, v154
	v_add_f32_e32 v152, 1.0, v152
	v_rcp_f32_e32 v148, v148
	v_rcp_f32_e32 v150, v150
	v_add_f32_e32 v158, 1.0, v158
	v_add_f32_e32 v160, 1.0, v160
	v_rcp_f32_e32 v156, v156
	v_rcp_f32_e32 v152, v152
	v_rcp_f32_e32 v158, v158
	v_rcp_f32_e32 v160, v160
	v_mul_f32_e32 v162, v159, v162
	v_mul_f32_e32 v164, v161, v164
	v_mul_f32_e32 v166, v163, v165
	v_mul_f32_e32 v144, v121, v144
	v_mul_f32_e32 v146, v145, v146
	v_mul_f32_e32 v154, v151, v154
	v_pk_fma_f32 v[22:23], v[122:123], v[162:163], v[22:23] op_sel_hi:[1,0,1]
	v_pk_fma_f32 v[12:13], v[122:123], v[164:165], v[12:13] op_sel_hi:[1,0,1]
	v_pk_fma_f32 v[20:21], v[124:125], v[162:163], v[20:21] op_sel_hi:[1,0,1]
	v_pk_fma_f32 v[10:11], v[124:125], v[164:165], v[10:11] op_sel_hi:[1,0,1]
	v_pk_fma_f32 v[16:17], v[122:123], v[166:167], v[16:17] op_sel_hi:[1,0,1]
	v_pk_fma_f32 v[14:15], v[124:125], v[166:167], v[14:15] op_sel_hi:[1,0,1]
	v_mul_f32_e32 v148, v131, v148
	v_mul_f32_e32 v150, v147, v150
	v_mul_f32_e32 v156, v153, v156
	s_waitcnt vmcnt(18)
	v_pk_fma_f32 v[22:23], v[132:133], v[144:145], v[22:23] op_sel_hi:[1,0,1]
	v_pk_fma_f32 v[12:13], v[132:133], v[146:147], v[12:13] op_sel_hi:[1,0,1]
	v_pk_fma_f32 v[20:21], v[134:135], v[144:145], v[20:21] op_sel_hi:[1,0,1]
	v_pk_fma_f32 v[10:11], v[134:135], v[146:147], v[10:11] op_sel_hi:[1,0,1]
	v_pk_fma_f32 v[16:17], v[132:133], v[154:155], v[16:17] op_sel_hi:[1,0,1]
	v_pk_fma_f32 v[14:15], v[134:135], v[154:155], v[14:15] op_sel_hi:[1,0,1]
	v_mul_f32_e32 v152, v149, v152
	v_mul_f32_e32 v158, v157, v158
	v_mul_f32_e32 v160, v155, v160
	s_waitcnt vmcnt(17)
	v_pk_fma_f32 v[22:23], v[136:137], v[148:149], v[22:23] op_sel_hi:[1,0,1]
	v_pk_fma_f32 v[12:13], v[136:137], v[150:151], v[12:13] op_sel_hi:[1,0,1]
	v_pk_fma_f32 v[20:21], v[138:139], v[148:149], v[20:21] op_sel_hi:[1,0,1]
	v_pk_fma_f32 v[10:11], v[138:139], v[150:151], v[10:11] op_sel_hi:[1,0,1]
	v_pk_fma_f32 v[16:17], v[136:137], v[156:157], v[16:17] op_sel_hi:[1,0,1]
	v_pk_fma_f32 v[14:15], v[138:139], v[156:157], v[14:15] op_sel_hi:[1,0,1]
	s_waitcnt vmcnt(16)
	v_pk_fma_f32 v[22:23], v[140:141], v[158:159], v[22:23] op_sel_hi:[1,0,1]
	v_pk_fma_f32 v[12:13], v[140:141], v[152:153], v[12:13] op_sel_hi:[1,0,1]
	v_pk_fma_f32 v[20:21], v[142:143], v[158:159], v[20:21] op_sel_hi:[1,0,1]
	v_pk_fma_f32 v[10:11], v[142:143], v[152:153], v[10:11] op_sel_hi:[1,0,1]
	v_pk_fma_f32 v[16:17], v[140:141], v[160:161], v[16:17] op_sel_hi:[1,0,1]
	v_pk_fma_f32 v[14:15], v[142:143], v[160:161], v[14:15] op_sel_hi:[1,0,1]
	s_waitcnt vmcnt(15)
	v_mul_f32_e32 v48, 0xbfb8aa3b, v25
	s_waitcnt vmcnt(14)
	v_mul_f32_e32 v50, 0xbfb8aa3b, v49
	s_waitcnt vmcnt(10)
	v_mul_f32_e32 v58, 0xbfb8aa3b, v55
	v_mul_f32_e32 v52, 0xbfb8aa3b, v35
	v_mul_f32_e32 v54, 0xbfb8aa3b, v51
	v_exp_f32_e32 v48, v48
	v_exp_f32_e32 v50, v50
	s_waitcnt vmcnt(5)
	v_mul_f32_e32 v66, 0xbfb8aa3b, v63
	s_waitcnt vmcnt(4)
	v_mul_f32_e32 v68, 0xbfb8aa3b, v65
	v_exp_f32_e32 v66, v66
	v_exp_f32_e32 v68, v68
	v_mul_f32_e32 v60, 0xbfb8aa3b, v57
	s_waitcnt vmcnt(3)
	v_mul_f32_e32 v69, 0xbfb8aa3b, v67
	v_exp_f32_e32 v69, v69
	v_exp_f32_e32 v58, v58
	v_mul_f32_e32 v56, 0xbfb8aa3b, v53
	v_exp_f32_e32 v52, v52
	v_exp_f32_e32 v54, v54
	v_mul_f32_e32 v62, 0xbfb8aa3b, v61
	v_mul_f32_e32 v64, 0xbfb8aa3b, v59
	v_exp_f32_e32 v60, v60
	v_exp_f32_e32 v56, v56
	v_exp_f32_e32 v62, v62
	v_exp_f32_e32 v64, v64
	v_add_f32_e32 v66, 1.0, v66
	v_add_f32_e32 v68, 1.0, v68
	v_add_f32_e32 v69, 1.0, v69
	v_add_f32_e32 v48, 1.0, v48
	v_add_f32_e32 v50, 1.0, v50
	v_add_f32_e32 v58, 1.0, v58
	v_rcp_f32_e32 v66, v66
	v_rcp_f32_e32 v68, v68
	v_rcp_f32_e32 v69, v69
	v_add_f32_e32 v52, 1.0, v52
	v_add_f32_e32 v54, 1.0, v54
	v_rcp_f32_e32 v48, v48
	v_rcp_f32_e32 v50, v50
	v_add_f32_e32 v60, 1.0, v60
	v_rcp_f32_e32 v58, v58
	v_add_f32_e32 v56, 1.0, v56
	v_rcp_f32_e32 v52, v52
	v_rcp_f32_e32 v54, v54
	v_add_f32_e32 v62, 1.0, v62
	v_add_f32_e32 v64, 1.0, v64
	v_rcp_f32_e32 v60, v60
	v_rcp_f32_e32 v56, v56
	v_rcp_f32_e32 v62, v62
	v_rcp_f32_e32 v64, v64
	v_mul_f32_e32 v66, v63, v66
	v_mul_f32_e32 v68, v65, v68
	v_mul_f32_e32 v70, v67, v69
	v_mul_f32_e32 v48, v25, v48
	v_mul_f32_e32 v50, v49, v50
	v_mul_f32_e32 v58, v55, v58
	v_pk_fma_f32 v[22:23], v[26:27], v[66:67], v[22:23] op_sel_hi:[1,0,1]
	v_pk_fma_f32 v[12:13], v[26:27], v[68:69], v[12:13] op_sel_hi:[1,0,1]
	v_pk_fma_f32 v[20:21], v[28:29], v[66:67], v[20:21] op_sel_hi:[1,0,1]
	v_pk_fma_f32 v[10:11], v[28:29], v[68:69], v[10:11] op_sel_hi:[1,0,1]
	v_pk_fma_f32 v[16:17], v[26:27], v[70:71], v[16:17] op_sel_hi:[1,0,1]
	v_pk_fma_f32 v[14:15], v[28:29], v[70:71], v[14:15] op_sel_hi:[1,0,1]
	v_mul_f32_e32 v52, v35, v52
	v_mul_f32_e32 v54, v51, v54
	v_mul_f32_e32 v60, v57, v60
	s_waitcnt vmcnt(2)
	v_pk_fma_f32 v[22:23], v[36:37], v[48:49], v[22:23] op_sel_hi:[1,0,1]
	v_pk_fma_f32 v[12:13], v[36:37], v[50:51], v[12:13] op_sel_hi:[1,0,1]
	v_pk_fma_f32 v[20:21], v[38:39], v[48:49], v[20:21] op_sel_hi:[1,0,1]
	v_pk_fma_f32 v[10:11], v[38:39], v[50:51], v[10:11] op_sel_hi:[1,0,1]
	v_pk_fma_f32 v[16:17], v[36:37], v[58:59], v[16:17] op_sel_hi:[1,0,1]
	v_pk_fma_f32 v[14:15], v[38:39], v[58:59], v[14:15] op_sel_hi:[1,0,1]
	v_mul_f32_e32 v56, v53, v56
	v_mul_f32_e32 v62, v61, v62
	v_mul_f32_e32 v64, v59, v64
	s_waitcnt vmcnt(1)
	v_pk_fma_f32 v[22:23], v[40:41], v[52:53], v[22:23] op_sel_hi:[1,0,1]
	v_pk_fma_f32 v[12:13], v[40:41], v[54:55], v[12:13] op_sel_hi:[1,0,1]
	v_pk_fma_f32 v[20:21], v[42:43], v[52:53], v[20:21] op_sel_hi:[1,0,1]
	v_pk_fma_f32 v[10:11], v[42:43], v[54:55], v[10:11] op_sel_hi:[1,0,1]
	v_pk_fma_f32 v[16:17], v[40:41], v[60:61], v[16:17] op_sel_hi:[1,0,1]
	v_pk_fma_f32 v[14:15], v[42:43], v[60:61], v[14:15] op_sel_hi:[1,0,1]
	s_waitcnt vmcnt(0)
	v_pk_fma_f32 v[22:23], v[44:45], v[62:63], v[22:23] op_sel_hi:[1,0,1]
	v_pk_fma_f32 v[12:13], v[44:45], v[56:57], v[12:13] op_sel_hi:[1,0,1]
	v_pk_fma_f32 v[20:21], v[46:47], v[62:63], v[20:21] op_sel_hi:[1,0,1]
	v_pk_fma_f32 v[10:11], v[46:47], v[56:57], v[10:11] op_sel_hi:[1,0,1]
	v_pk_fma_f32 v[16:17], v[44:45], v[64:65], v[16:17] op_sel_hi:[1,0,1]
	v_pk_fma_f32 v[14:15], v[46:47], v[64:65], v[14:15] op_sel_hi:[1,0,1]
	ds_bpermute_b32 v6, v3, v22
	ds_bpermute_b32 v7, v3, v23
	ds_bpermute_b32 v18, v3, v20
	ds_bpermute_b32 v19, v3, v21
	ds_bpermute_b32 v24, v3, v14
	ds_bpermute_b32 v25, v3, v15
	s_waitcnt lgkmcnt(4)
	v_pk_add_f32 v[6:7], v[22:23], v[6:7]
	ds_bpermute_b32 v22, v3, v16
	ds_bpermute_b32 v23, v3, v17
	ds_bpermute_b32 v26, v3, v12
	ds_bpermute_b32 v27, v3, v13
	ds_bpermute_b32 v28, v3, v10
	ds_bpermute_b32 v29, v3, v11
	s_waitcnt lgkmcnt(8)
	v_pk_add_f32 v[18:19], v[20:21], v[18:19]
	s_waitcnt lgkmcnt(4)
	v_pk_add_f32 v[16:17], v[16:17], v[22:23]
	v_pk_add_f32 v[14:15], v[14:15], v[24:25]
	s_waitcnt lgkmcnt(2)
	v_pk_add_f32 v[12:13], v[12:13], v[26:27]
	s_waitcnt lgkmcnt(0)
	v_pk_add_f32 v[10:11], v[10:11], v[28:29]
	ds_bpermute_b32 v8, v30, v6
	ds_bpermute_b32 v9, v30, v7
	ds_bpermute_b32 v20, v30, v18
	ds_bpermute_b32 v21, v30, v19
	ds_bpermute_b32 v22, v30, v16
	ds_bpermute_b32 v23, v30, v17
	ds_bpermute_b32 v24, v30, v14
	ds_bpermute_b32 v25, v30, v15
	ds_bpermute_b32 v26, v30, v12
	ds_bpermute_b32 v27, v30, v13
	ds_bpermute_b32 v28, v30, v10
	ds_bpermute_b32 v29, v30, v11
	s_and_saveexec_b64 s[12:13], s[2:3]
	s_cbranch_execz .LBB0_28
	s_waitcnt lgkmcnt(10)
	v_pk_add_f32 v[6:7], v[6:7], v[8:9]
	s_waitcnt lgkmcnt(8)
	v_pk_add_f32 v[8:9], v[18:19], v[20:21]
	ds_write_b128 v33, v[6:9]
	s_waitcnt lgkmcnt(7)
	v_pk_add_f32 v[6:7], v[16:17], v[22:23]
	s_waitcnt lgkmcnt(5)
	v_pk_add_f32 v[8:9], v[14:15], v[24:25]
	ds_write_b128 v33, v[6:9] offset:256
	s_waitcnt lgkmcnt(4)
	v_pk_add_f32 v[6:7], v[12:13], v[26:27]
	s_waitcnt lgkmcnt(2)
	v_pk_add_f32 v[8:9], v[10:11], v[28:29]
	ds_write_b128 v33, v[6:9] offset:512
